# resid+norm epilogue: waves 1-7 store the f32 residual tile before the grid barrier so it drains during the barrier
# baseline (speedup 1.0000x reference)
.LBB0_532:
	v_and_b32_e32 v130, 64, v209
	s_lshl_b32 s6, s81, 8
	v_xor_b32_e32 v0, 16, v209
	v_add_u32_e32 v130, 64, v130
	s_add_i32 s6, s6, s47
	v_cmp_lt_i32_e32 vcc, v0, v130
	v_xor_b32_e32 v131, 32, v209
	s_lshl_b32 s0, s34, 5
	v_add_u32_e32 v194, s6, v145
	s_lshl_b32 s6, s84, 8
	v_cndmask_b32_e32 v0, v209, v0, vcc
	v_cmp_lt_i32_e32 vcc, v131, v130
	s_or_b32 s0, s6, s0
	v_ashrrev_i32_e32 v195, 31, v194
	v_cndmask_b32_e32 v130, v209, v131, vcc
	v_lshl_or_b32 v166, v144, 3, s0
	v_lshlrev_b32_e32 v172, 2, v130
	v_lshlrev_b64 v[130:131], 12, v[194:195]
	v_ashrrev_i32_e32 v167, 31, v166
	v_lshl_add_u64 v[130:131], s[16:17], 0, v[130:131]
	v_lshl_add_u64 v[138:139], v[166:167], 2, v[130:131]
	s_barrier
	v_lshlrev_b32_e32 v0, 2, v0
	v_mov_b32_e32 v251, v172
	v_cmp_eq_u32_e32 vcc, 0, v144
	v_lshlrev_b32_e32 v200, 12, v194
	v_lshl_add_u32 v200, v166, 2, v200
	s_lshl_b32 s6, s84, 2
	s_ashr_i32 s7, s6, 31
	s_lshl_b64 s[6:7], s[6:7], 2
	s_add_u32 s0, s22, s6
	s_addc_u32 s7, s23, s7
	s_lshl_b32 s6, s34, 2
	s_add_u32 s6, s0, s6
	s_addc_u32 s7, s7, 0
	v_readlane_b32 s28, v254, 39
	s_mov_b32 s98, s36
	s_mov_b32 s83, 0x800000
	v_readlane_b32 s29, v254, 40
	v_readlane_b32 s48, v254, 41
	s_mov_b64 s[34:35], s[50:51]
	v_readlane_b32 s49, v254, 42
	s_mov_b64 s[8:9], s[16:17]
	global_load_dwordx4 v[150:153], v200, s[8:9]
	global_load_dwordx4 v[146:149], v200, s[8:9] offset:16
	global_load_dwordx4 v[154:157], v200, s[8:9] offset:512
	global_load_dwordx4 v[158:161], v200, s[8:9] offset:528
	s_add_u32 s8, s16, 0x10000
	s_addc_u32 s9, s17, 0
	global_load_dwordx4 v[134:137], v200, s[8:9]
	global_load_dwordx4 v[130:133], v200, s[8:9] offset:16
	global_load_dwordx4 v[138:141], v200, s[8:9] offset:512
	global_load_dwordx4 v[142:145], v200, s[8:9] offset:528
	s_add_u32 s8, s16, 0x20000
	s_addc_u32 s9, s17, 0
	global_load_dwordx4 v[210:213], v200, s[8:9]
	global_load_dwordx4 v[214:217], v200, s[8:9] offset:16
	global_load_dwordx4 v[218:221], v200, s[8:9] offset:512
	global_load_dwordx4 v[222:225], v200, s[8:9] offset:528
	s_add_u32 s8, s16, 0x30000
	s_addc_u32 s9, s17, 0
	global_load_dwordx4 v[226:229], v200, s[8:9]
	global_load_dwordx4 v[230:233], v200, s[8:9] offset:16
	global_load_dwordx4 v[234:237], v200, s[8:9] offset:512
	global_load_dwordx4 v[238:241], v200, s[8:9] offset:528
	s_waitcnt vmcnt(12)
	v_pk_fma_f32 v[150:151], s[18:19], v[126:127], v[150:151]
	v_pk_fma_f32 v[152:153], s[24:25], v[128:129], v[152:153]
	v_pk_fma_f32 v[146:147], s[18:19], v[122:123], v[146:147]
	v_pk_fma_f32 v[148:149], s[24:25], v[124:125], v[148:149]
	v_pk_fma_f32 v[154:155], s[18:19], v[118:119], v[154:155]
	v_pk_fma_f32 v[156:157], s[24:25], v[120:121], v[156:157]
	v_pk_fma_f32 v[158:159], s[18:19], v[114:115], v[158:159]
	v_pk_fma_f32 v[160:161], s[24:25], v[116:117], v[160:161]
	v_mul_f32_e32 v202, v153, v153
	v_mul_f32_e32 v201, v151, v151
	v_fmac_f32_e32 v201, v150, v150
	v_fmac_f32_e32 v202, v152, v152
	v_add_f32_e32 v201, v201, v202
	v_mul_f32_e32 v206, v149, v149
	v_mul_f32_e32 v203, v147, v147
	v_fmac_f32_e32 v203, v146, v146
	v_fmac_f32_e32 v206, v148, v148
	v_add_f32_e32 v203, v203, v206
	v_add_f32_e32 v201, v201, v203
	v_mul_f32_e32 v206, v157, v157
	v_mul_f32_e32 v203, v155, v155
	v_fmac_f32_e32 v203, v154, v154
	v_fmac_f32_e32 v206, v156, v156
	v_add_f32_e32 v203, v203, v206
	v_mul_f32_e32 v206, v161, v161
	v_mul_f32_e32 v202, v159, v159
	v_fmac_f32_e32 v202, v158, v158
	v_fmac_f32_e32 v206, v160, v160
	v_add_f32_e32 v202, v202, v206
	v_add_f32_e32 v203, v203, v202
	v_add_f32_e32 v242, v201, v203
	s_add_u32 s8, s16, 0x80000
	s_addc_u32 s9, s17, 0
	global_load_dwordx4 v[114:117], v200, s[8:9]
	global_load_dwordx4 v[118:121], v200, s[8:9] offset:16
	global_load_dwordx4 v[122:125], v200, s[8:9] offset:512
	global_load_dwordx4 v[126:129], v200, s[8:9] offset:528
	s_waitcnt vmcnt(12)
	v_pk_fma_f32 v[134:135], s[18:19], v[110:111], v[134:135]
	v_pk_fma_f32 v[136:137], s[24:25], v[112:113], v[136:137]
	v_pk_fma_f32 v[130:131], s[18:19], v[106:107], v[130:131]
	v_pk_fma_f32 v[132:133], s[24:25], v[108:109], v[132:133]
	v_pk_fma_f32 v[138:139], s[18:19], v[102:103], v[138:139]
	v_pk_fma_f32 v[140:141], s[24:25], v[104:105], v[140:141]
	v_pk_fma_f32 v[142:143], s[18:19], v[98:99], v[142:143]
	v_pk_fma_f32 v[144:145], s[24:25], v[100:101], v[144:145]
	v_mul_f32_e32 v202, v137, v137
	v_mul_f32_e32 v201, v135, v135
	v_fmac_f32_e32 v201, v134, v134
	v_fmac_f32_e32 v202, v136, v136
	v_add_f32_e32 v201, v201, v202
	v_mul_f32_e32 v206, v133, v133
	v_mul_f32_e32 v203, v131, v131
	v_fmac_f32_e32 v203, v130, v130
	v_fmac_f32_e32 v206, v132, v132
	v_add_f32_e32 v203, v203, v206
	v_add_f32_e32 v201, v201, v203
	v_mul_f32_e32 v206, v141, v141
	v_mul_f32_e32 v203, v139, v139
	v_fmac_f32_e32 v203, v138, v138
	v_fmac_f32_e32 v206, v140, v140
	v_add_f32_e32 v203, v203, v206
	v_mul_f32_e32 v206, v145, v145
	v_mul_f32_e32 v202, v143, v143
	v_fmac_f32_e32 v202, v142, v142
	v_fmac_f32_e32 v206, v144, v144
	v_add_f32_e32 v202, v202, v206
	v_add_f32_e32 v203, v203, v202
	v_add_f32_e32 v243, v201, v203
	s_add_u32 s8, s16, 0x90000
	s_addc_u32 s9, s17, 0
	global_load_dwordx4 v[98:101], v200, s[8:9]
	global_load_dwordx4 v[102:105], v200, s[8:9] offset:16
	global_load_dwordx4 v[106:109], v200, s[8:9] offset:512
	global_load_dwordx4 v[110:113], v200, s[8:9] offset:528
	s_waitcnt vmcnt(12)
	v_pk_fma_f32 v[86:87], s[18:19], v[86:87], v[210:211]
	v_pk_fma_f32 v[88:89], s[24:25], v[88:89], v[212:213]
	v_pk_fma_f32 v[82:83], s[18:19], v[82:83], v[214:215]
	v_pk_fma_f32 v[84:85], s[24:25], v[84:85], v[216:217]
	v_pk_fma_f32 v[90:91], s[18:19], v[90:91], v[218:219]
	v_pk_fma_f32 v[92:93], s[24:25], v[92:93], v[220:221]
	v_pk_fma_f32 v[94:95], s[18:19], v[94:95], v[222:223]
	v_pk_fma_f32 v[96:97], s[24:25], v[96:97], v[224:225]
	v_mul_f32_e32 v202, v89, v89
	v_mul_f32_e32 v201, v87, v87
	v_fmac_f32_e32 v201, v86, v86
	v_fmac_f32_e32 v202, v88, v88
	v_add_f32_e32 v201, v201, v202
	v_mul_f32_e32 v206, v85, v85
	v_mul_f32_e32 v203, v83, v83
	v_fmac_f32_e32 v203, v82, v82
	v_fmac_f32_e32 v206, v84, v84
	v_add_f32_e32 v203, v203, v206
	v_add_f32_e32 v201, v201, v203
	v_mul_f32_e32 v206, v93, v93
	v_mul_f32_e32 v203, v91, v91
	v_fmac_f32_e32 v203, v90, v90
	v_fmac_f32_e32 v206, v92, v92
	v_add_f32_e32 v203, v203, v206
	v_mul_f32_e32 v206, v97, v97
	v_mul_f32_e32 v202, v95, v95
	v_fmac_f32_e32 v202, v94, v94
	v_fmac_f32_e32 v206, v96, v96
	v_add_f32_e32 v202, v202, v206
	v_add_f32_e32 v203, v203, v202
	v_add_f32_e32 v244, v201, v203
	s_add_u32 s8, s16, 0xa0000
	s_addc_u32 s9, s17, 0
	global_load_dwordx4 v[210:213], v200, s[8:9]
	global_load_dwordx4 v[214:217], v200, s[8:9] offset:16
	global_load_dwordx4 v[218:221], v200, s[8:9] offset:512
	global_load_dwordx4 v[222:225], v200, s[8:9] offset:528
	s_waitcnt vmcnt(12)
	v_pk_fma_f32 v[70:71], s[18:19], v[70:71], v[226:227]
	v_pk_fma_f32 v[72:73], s[24:25], v[72:73], v[228:229]
	v_pk_fma_f32 v[66:67], s[18:19], v[66:67], v[230:231]
	v_pk_fma_f32 v[68:69], s[24:25], v[68:69], v[232:233]
	v_pk_fma_f32 v[74:75], s[18:19], v[74:75], v[234:235]
	v_pk_fma_f32 v[76:77], s[24:25], v[76:77], v[236:237]
	v_pk_fma_f32 v[78:79], s[18:19], v[78:79], v[238:239]
	v_pk_fma_f32 v[80:81], s[24:25], v[80:81], v[240:241]
	v_mul_f32_e32 v202, v73, v73
	v_mul_f32_e32 v201, v71, v71
	v_fmac_f32_e32 v201, v70, v70
	v_fmac_f32_e32 v202, v72, v72
	v_add_f32_e32 v201, v201, v202
	v_mul_f32_e32 v206, v69, v69
	v_mul_f32_e32 v203, v67, v67
	v_fmac_f32_e32 v203, v66, v66
	v_fmac_f32_e32 v206, v68, v68
	v_add_f32_e32 v203, v203, v206
	v_add_f32_e32 v201, v201, v203
	v_mul_f32_e32 v206, v77, v77
	v_mul_f32_e32 v203, v75, v75
	v_fmac_f32_e32 v203, v74, v74
	v_fmac_f32_e32 v206, v76, v76
	v_add_f32_e32 v203, v203, v206
	v_mul_f32_e32 v206, v81, v81
	v_mul_f32_e32 v202, v79, v79
	v_fmac_f32_e32 v202, v78, v78
	v_fmac_f32_e32 v206, v80, v80
	v_add_f32_e32 v202, v202, v206
	v_add_f32_e32 v203, v203, v202
	v_add_f32_e32 v245, v201, v203
	s_add_u32 s8, s16, 0xb0000
	s_addc_u32 s9, s17, 0
	global_load_dwordx4 v[226:229], v200, s[8:9]
	global_load_dwordx4 v[230:233], v200, s[8:9] offset:16
	global_load_dwordx4 v[234:237], v200, s[8:9] offset:512
	global_load_dwordx4 v[238:241], v200, s[8:9] offset:528
	s_waitcnt vmcnt(12)
	v_pk_fma_f32 v[54:55], s[18:19], v[54:55], v[114:115]
	v_pk_fma_f32 v[56:57], s[24:25], v[56:57], v[116:117]
	v_pk_fma_f32 v[50:51], s[18:19], v[50:51], v[118:119]
	v_pk_fma_f32 v[52:53], s[24:25], v[52:53], v[120:121]
	v_pk_fma_f32 v[58:59], s[18:19], v[58:59], v[122:123]
	v_pk_fma_f32 v[60:61], s[24:25], v[60:61], v[124:125]
	v_pk_fma_f32 v[62:63], s[18:19], v[62:63], v[126:127]
	v_pk_fma_f32 v[64:65], s[24:25], v[64:65], v[128:129]
	v_mul_f32_e32 v202, v57, v57
	v_mul_f32_e32 v201, v55, v55
	v_fmac_f32_e32 v201, v54, v54
	v_fmac_f32_e32 v202, v56, v56
	v_add_f32_e32 v201, v201, v202
	v_mul_f32_e32 v206, v53, v53
	v_mul_f32_e32 v203, v51, v51
	v_fmac_f32_e32 v203, v50, v50
	v_fmac_f32_e32 v206, v52, v52
	v_add_f32_e32 v203, v203, v206
	v_add_f32_e32 v201, v201, v203
	v_mul_f32_e32 v206, v61, v61
	v_mul_f32_e32 v203, v59, v59
	v_fmac_f32_e32 v203, v58, v58
	v_fmac_f32_e32 v206, v60, v60
	v_add_f32_e32 v203, v203, v206
	v_mul_f32_e32 v206, v65, v65
	v_mul_f32_e32 v202, v63, v63
	v_fmac_f32_e32 v202, v62, v62
	v_fmac_f32_e32 v206, v64, v64
	v_add_f32_e32 v202, v202, v206
	v_add_f32_e32 v203, v203, v202
	v_add_f32_e32 v246, v201, v203
	s_waitcnt vmcnt(8)
	v_pk_fma_f32 v[38:39], s[18:19], v[38:39], v[98:99]
	v_pk_fma_f32 v[40:41], s[24:25], v[40:41], v[100:101]
	v_pk_fma_f32 v[34:35], s[18:19], v[34:35], v[102:103]
	v_pk_fma_f32 v[36:37], s[24:25], v[36:37], v[104:105]
	v_pk_fma_f32 v[42:43], s[18:19], v[42:43], v[106:107]
	v_pk_fma_f32 v[44:45], s[24:25], v[44:45], v[108:109]
	v_pk_fma_f32 v[46:47], s[18:19], v[46:47], v[110:111]
	v_pk_fma_f32 v[48:49], s[24:25], v[48:49], v[112:113]
	v_mul_f32_e32 v202, v41, v41
	v_mul_f32_e32 v201, v39, v39
	v_fmac_f32_e32 v201, v38, v38
	v_fmac_f32_e32 v202, v40, v40
	v_add_f32_e32 v201, v201, v202
	v_mul_f32_e32 v206, v37, v37
	v_mul_f32_e32 v203, v35, v35
	v_fmac_f32_e32 v203, v34, v34
	v_fmac_f32_e32 v206, v36, v36
	v_add_f32_e32 v203, v203, v206
	v_add_f32_e32 v201, v201, v203
	v_mul_f32_e32 v206, v45, v45
	v_mul_f32_e32 v203, v43, v43
	v_fmac_f32_e32 v203, v42, v42
	v_fmac_f32_e32 v206, v44, v44
	v_add_f32_e32 v203, v203, v206
	v_mul_f32_e32 v206, v49, v49
	v_mul_f32_e32 v202, v47, v47
	v_fmac_f32_e32 v202, v46, v46
	v_fmac_f32_e32 v206, v48, v48
	v_add_f32_e32 v202, v202, v206
	v_add_f32_e32 v203, v203, v202
	v_add_f32_e32 v247, v201, v203
	s_waitcnt vmcnt(4)
	v_pk_fma_f32 v[22:23], s[18:19], v[22:23], v[210:211]
	v_pk_fma_f32 v[24:25], s[24:25], v[24:25], v[212:213]
	v_pk_fma_f32 v[18:19], s[18:19], v[18:19], v[214:215]
	v_pk_fma_f32 v[20:21], s[24:25], v[20:21], v[216:217]
	v_pk_fma_f32 v[26:27], s[18:19], v[26:27], v[218:219]
	v_pk_fma_f32 v[28:29], s[24:25], v[28:29], v[220:221]
	v_pk_fma_f32 v[30:31], s[18:19], v[30:31], v[222:223]
	v_pk_fma_f32 v[32:33], s[24:25], v[32:33], v[224:225]
	v_mul_f32_e32 v202, v25, v25
	v_mul_f32_e32 v201, v23, v23
	v_fmac_f32_e32 v201, v22, v22
	v_fmac_f32_e32 v202, v24, v24
	v_add_f32_e32 v201, v201, v202
	v_mul_f32_e32 v206, v21, v21
	v_mul_f32_e32 v203, v19, v19
	v_fmac_f32_e32 v203, v18, v18
	v_fmac_f32_e32 v206, v20, v20
	v_add_f32_e32 v203, v203, v206
	v_add_f32_e32 v201, v201, v203
	v_mul_f32_e32 v206, v29, v29
	v_mul_f32_e32 v203, v27, v27
	v_fmac_f32_e32 v203, v26, v26
	v_fmac_f32_e32 v206, v28, v28
	v_add_f32_e32 v203, v203, v206
	v_mul_f32_e32 v206, v33, v33
	v_mul_f32_e32 v202, v31, v31
	v_fmac_f32_e32 v202, v30, v30
	v_fmac_f32_e32 v206, v32, v32
	v_add_f32_e32 v202, v202, v206
	v_add_f32_e32 v203, v203, v202
	v_add_f32_e32 v248, v201, v203
	s_waitcnt vmcnt(0)
	v_pk_fma_f32 v[6:7], s[18:19], v[6:7], v[226:227]
	v_pk_fma_f32 v[8:9], s[24:25], v[8:9], v[228:229]
	v_pk_fma_f32 v[2:3], s[18:19], v[2:3], v[230:231]
	v_pk_fma_f32 v[4:5], s[24:25], v[4:5], v[232:233]
	v_pk_fma_f32 v[10:11], s[18:19], v[10:11], v[234:235]
	v_pk_fma_f32 v[12:13], s[24:25], v[12:13], v[236:237]
	v_pk_fma_f32 v[14:15], s[18:19], v[14:15], v[238:239]
	v_pk_fma_f32 v[16:17], s[24:25], v[16:17], v[240:241]
	v_mul_f32_e32 v202, v9, v9
	v_mul_f32_e32 v201, v7, v7
	v_fmac_f32_e32 v201, v6, v6
	v_fmac_f32_e32 v202, v8, v8
	v_add_f32_e32 v201, v201, v202
	v_mul_f32_e32 v206, v5, v5
	v_mul_f32_e32 v203, v3, v3
	v_fmac_f32_e32 v203, v2, v2
	v_fmac_f32_e32 v206, v4, v4
	v_add_f32_e32 v203, v203, v206
	v_add_f32_e32 v201, v201, v203
	v_mul_f32_e32 v206, v13, v13
	v_mul_f32_e32 v203, v11, v11
	v_fmac_f32_e32 v203, v10, v10
	v_fmac_f32_e32 v206, v12, v12
	v_add_f32_e32 v203, v203, v206
	v_mul_f32_e32 v206, v17, v17
	v_mul_f32_e32 v202, v15, v15
	v_fmac_f32_e32 v202, v14, v14
	v_fmac_f32_e32 v206, v16, v16
	v_add_f32_e32 v202, v202, v206
	v_add_f32_e32 v203, v203, v202
	v_add_f32_e32 v249, v201, v203
	ds_bpermute_b32 v168, v0, v242
	ds_bpermute_b32 v169, v0, v243
	ds_bpermute_b32 v170, v0, v244
	ds_bpermute_b32 v171, v0, v245
	ds_bpermute_b32 v172, v0, v246
	ds_bpermute_b32 v173, v0, v247
	ds_bpermute_b32 v174, v0, v248
	ds_bpermute_b32 v175, v0, v249
	s_waitcnt lgkmcnt(0)
	v_add_f32_e32 v242, v242, v168
	v_add_f32_e32 v243, v243, v169
	v_add_f32_e32 v244, v244, v170
	v_add_f32_e32 v245, v245, v171
	v_add_f32_e32 v246, v246, v172
	v_add_f32_e32 v247, v247, v173
	v_add_f32_e32 v248, v248, v174
	v_add_f32_e32 v249, v249, v175
	ds_bpermute_b32 v168, v251, v242
	ds_bpermute_b32 v169, v251, v243
	ds_bpermute_b32 v170, v251, v244
	ds_bpermute_b32 v171, v251, v245
	ds_bpermute_b32 v172, v251, v246
	ds_bpermute_b32 v173, v251, v247
	ds_bpermute_b32 v174, v251, v248
	ds_bpermute_b32 v175, v251, v249
	v_lshlrev_b32_e32 v201, 6, v194
	v_add_u32_e32 v202, 0x2000, v201
	s_waitcnt lgkmcnt(0)
	v_add_f32_e32 v242, v242, v168
	v_add_f32_e32 v243, v243, v169
	v_add_f32_e32 v244, v244, v170
	v_add_f32_e32 v245, v245, v171
	v_add_f32_e32 v246, v246, v172
	v_add_f32_e32 v247, v247, v173
	v_add_f32_e32 v248, v248, v174
	v_add_f32_e32 v249, v249, v175
	s_and_saveexec_b64 s[8:9], vcc
	global_store_dword v201, v242, s[6:7]
	global_store_dword v201, v243, s[6:7] offset:1024
	global_store_dword v201, v244, s[6:7] offset:2048
	global_store_dword v201, v245, s[6:7] offset:3072
	global_store_dword v202, v246, s[6:7]
	global_store_dword v202, v247, s[6:7] offset:1024
	global_store_dword v202, v248, s[6:7] offset:2048
	global_store_dword v202, v249, s[6:7] offset:3072
	s_or_b64 exec, exec, s[8:9]
	s_cmp_lt_u32 s74, 64
	s_cbranch_scc1 .Lrn_w0
	v_readlane_b32 s6, v254, 6
	v_readlane_b32 s7, v254, 7
	s_nop 4
	v_mov_b32_e32 v201, v200
	global_store_dwordx4 v201, v[150:153], s[6:7] nt
	global_store_dwordx4 v201, v[146:149], s[6:7] offset:16 nt
	global_store_dwordx4 v201, v[154:157], s[6:7] offset:512 nt
	global_store_dwordx4 v201, v[158:161], s[6:7] offset:528 nt
	v_add_u32_e32 v201, 0x10000, v200
	global_store_dwordx4 v201, v[134:137], s[6:7] nt
	global_store_dwordx4 v201, v[130:133], s[6:7] offset:16 nt
	global_store_dwordx4 v201, v[138:141], s[6:7] offset:512 nt
	global_store_dwordx4 v201, v[142:145], s[6:7] offset:528 nt
	v_add_u32_e32 v201, 0x20000, v200
	global_store_dwordx4 v201, v[86:89], s[6:7] nt
	global_store_dwordx4 v201, v[82:85], s[6:7] offset:16 nt
	global_store_dwordx4 v201, v[90:93], s[6:7] offset:512 nt
	global_store_dwordx4 v201, v[94:97], s[6:7] offset:528 nt
	v_add_u32_e32 v201, 0x30000, v200
	global_store_dwordx4 v201, v[70:73], s[6:7] nt
	global_store_dwordx4 v201, v[66:69], s[6:7] offset:16 nt
	global_store_dwordx4 v201, v[74:77], s[6:7] offset:512 nt
	global_store_dwordx4 v201, v[78:81], s[6:7] offset:528 nt
	v_add_u32_e32 v201, 0x80000, v200
	global_store_dwordx4 v201, v[54:57], s[6:7] nt
	global_store_dwordx4 v201, v[50:53], s[6:7] offset:16 nt
	global_store_dwordx4 v201, v[58:61], s[6:7] offset:512 nt
	global_store_dwordx4 v201, v[62:65], s[6:7] offset:528 nt
	v_add_u32_e32 v201, 0x90000, v200
	global_store_dwordx4 v201, v[38:41], s[6:7] nt
	global_store_dwordx4 v201, v[34:37], s[6:7] offset:16 nt
	global_store_dwordx4 v201, v[42:45], s[6:7] offset:512 nt
	global_store_dwordx4 v201, v[46:49], s[6:7] offset:528 nt
	v_add_u32_e32 v201, 0xa0000, v200
	global_store_dwordx4 v201, v[22:25], s[6:7] nt
	global_store_dwordx4 v201, v[18:21], s[6:7] offset:16 nt
	global_store_dwordx4 v201, v[26:29], s[6:7] offset:512 nt
	global_store_dwordx4 v201, v[30:33], s[6:7] offset:528 nt
	v_add_u32_e32 v201, 0xb0000, v200
	global_store_dwordx4 v201, v[6:9], s[6:7] nt
	global_store_dwordx4 v201, v[2:5], s[6:7] offset:16 nt
	global_store_dwordx4 v201, v[10:13], s[6:7] offset:512 nt
	global_store_dwordx4 v201, v[14:17], s[6:7] offset:528 nt
	s_waitcnt vmcnt(32)
	s_branch .Lrn_wdone

.Lrn_wdone:
	s_getreg_b32 s0, hwreg(HW_REG_XCC_ID, 0, 4)
	s_waitcnt lgkmcnt(0)
	s_barrier
	s_mov_b64 s[6:7], exec
	v_readlane_b32 s8, v252, 4
	v_readlane_b32 s9, v252, 5
	s_and_b64 s[8:9], s[6:7], s[8:9]
	s_xor_b64 s[6:7], s[8:9], s[6:7]
	s_mov_b64 exec, s[8:9]
	s_cbranch_execz .LBB0_601
	v_readlane_b32 s8, v253, 9
	s_waitcnt vmcnt(0) expcnt(0) lgkmcnt(0)
	s_and_b32 s0, s0, 15
	v_mov_b32_e32 v0, s8
	ds_read_b32 v99, v0
	v_readlane_b32 s8, v253, 10
	s_waitcnt lgkmcnt(0)
	v_cmp_ne_u32_e32 vcc, 0, v99
	v_mov_b32_e32 v0, s8
	ds_read_b32 v98, v0
	s_cbranch_vccnz .LBB0_564
	s_mov_b32 s14, 1
	s_branch .LBB0_552

.LBB0_601:
	s_or_b64 exec, exec, s[6:7]
	s_mov_b64 s[84:85], s[62:63]
	s_mov_b64 s[80:81], s[60:61]
	s_mov_b64 s[74:75], s[58:59]
	s_mov_b64 s[28:29], s[56:57]
	s_mov_b64 s[14:15], s[54:55]
	s_mov_b64 s[10:11], s[52:53]
	v_readlane_b32 s6, v254, 27
	v_readlane_b32 s7, v254, 28
	v_readlane_b32 s8, v253, 38
	v_readlane_b32 s9, v253, 39
	v_readlane_b32 s48, v253, 56
	v_readlane_b32 s49, v253, 57
	v_readlane_b32 s50, v254, 8
	v_readlane_b32 s51, v254, 9
	v_readlane_b32 s52, v254, 6
	v_readlane_b32 s53, v254, 7
	v_readfirstlane_b32 s0, v204
	s_waitcnt lgkmcnt(0)
	s_barrier
	v_bfe_u32 v201, v204, 4, 2
	v_lshlrev_b32_e32 v202, 2, v166
	v_lshlrev_b32_e32 v203, 6, v194
	v_lshl_add_u32 v203, v201, 4, v203
	v_add_u32_e32 v206, 0x2000, v203
	v_xor_b32_e32 v207, 16, v209
	v_xor_b32_e32 v250, 32, v209
	v_lshlrev_b32_e32 v207, 2, v207
	v_lshlrev_b32_e32 v250, 2, v250
	global_load_dwordx4 v[210:213], v203, s[22:23]
	global_load_dwordx4 v[214:217], v203, s[22:23] offset:1024
	global_load_dwordx4 v[218:221], v203, s[22:23] offset:2048
	global_load_dwordx4 v[222:225], v203, s[22:23] offset:3072
	global_load_dwordx4 v[226:229], v206, s[22:23]
	global_load_dwordx4 v[230:233], v206, s[22:23] offset:1024
	global_load_dwordx4 v[234:237], v206, s[22:23] offset:2048
	global_load_dwordx4 v[238:241], v206, s[22:23] offset:3072
	global_load_dwordx4 v[122:125], v202, s[6:7]
	global_load_dwordx4 v[118:121], v202, s[6:7] offset:16
	global_load_dwordx4 v[110:113], v202, s[6:7] offset:512
	global_load_dwordx4 v[106:109], v202, s[6:7] offset:528
	s_and_b64 vcc, exec, s[8:9]
	s_cbranch_vccz .Lrn_g2_done
	global_load_dwordx4 v[114:117], v202, s[48:49]
	global_load_dwordx4 v[126:129], v202, s[48:49] offset:16
	global_load_dwordx4 v[98:101], v202, s[48:49] offset:512
	global_load_dwordx4 v[102:105], v202, s[48:49] offset:528
.Lrn_g2_done:
	v_lshlrev_b32_e32 v200, 12, v194
	v_lshl_add_u32 v200, v166, 2, v200
	v_lshlrev_b32_e32 v251, 11, v194
	v_lshl_add_u32 v251, v166, 1, v251
	v_readlane_b32 s6, v254, 10
	v_readlane_b32 s7, v254, 11
	s_waitcnt vmcnt(0)
	v_add_f32_e32 v210, v210, v211
	v_add_f32_e32 v212, v212, v213
	v_add_f32_e32 v242, v210, v212
	v_add_f32_e32 v214, v214, v215
	v_add_f32_e32 v216, v216, v217
	v_add_f32_e32 v243, v214, v216
	v_add_f32_e32 v218, v218, v219
	v_add_f32_e32 v220, v220, v221
	v_add_f32_e32 v244, v218, v220
	v_add_f32_e32 v222, v222, v223
	v_add_f32_e32 v224, v224, v225
	v_add_f32_e32 v245, v222, v224
	v_add_f32_e32 v226, v226, v227
	v_add_f32_e32 v228, v228, v229
	v_add_f32_e32 v246, v226, v228
	v_add_f32_e32 v230, v230, v231
	v_add_f32_e32 v232, v232, v233
	v_add_f32_e32 v247, v230, v232
	v_add_f32_e32 v234, v234, v235
	v_add_f32_e32 v236, v236, v237
	v_add_f32_e32 v248, v234, v236
	v_add_f32_e32 v238, v238, v239
	v_add_f32_e32 v240, v240, v241
	v_add_f32_e32 v249, v238, v240
	ds_bpermute_b32 v168, v207, v242
	ds_bpermute_b32 v169, v207, v243
	ds_bpermute_b32 v170, v207, v244
	ds_bpermute_b32 v171, v207, v245
	ds_bpermute_b32 v172, v207, v246
	ds_bpermute_b32 v173, v207, v247
	ds_bpermute_b32 v174, v207, v248
	ds_bpermute_b32 v175, v207, v249
	s_waitcnt lgkmcnt(0)
	v_add_f32_e32 v242, v242, v168
	v_add_f32_e32 v243, v243, v169
	v_add_f32_e32 v244, v244, v170
	v_add_f32_e32 v245, v245, v171
	v_add_f32_e32 v246, v246, v172
	v_add_f32_e32 v247, v247, v173
	v_add_f32_e32 v248, v248, v174
	v_add_f32_e32 v249, v249, v175
	ds_bpermute_b32 v168, v250, v242
	ds_bpermute_b32 v169, v250, v243
	ds_bpermute_b32 v170, v250, v244
	ds_bpermute_b32 v171, v250, v245
	ds_bpermute_b32 v172, v250, v246
	ds_bpermute_b32 v173, v250, v247
	ds_bpermute_b32 v174, v250, v248
	ds_bpermute_b32 v175, v250, v249
	s_waitcnt lgkmcnt(0)
	v_add_f32_e32 v242, v242, v168
	v_add_f32_e32 v243, v243, v169
	v_add_f32_e32 v244, v244, v170
	v_add_f32_e32 v245, v245, v171
	v_add_f32_e32 v246, v246, v172
	v_add_f32_e32 v247, v247, v173
	v_add_f32_e32 v248, v248, v174
	v_add_f32_e32 v249, v249, v175
	v_fmamk_f32 v242, v242, 0x3a800000, v205
	v_fmamk_f32 v243, v243, 0x3a800000, v205
	v_fmamk_f32 v244, v244, 0x3a800000, v205
	v_fmamk_f32 v245, v245, 0x3a800000, v205
	v_fmamk_f32 v246, v246, 0x3a800000, v205
	v_fmamk_f32 v247, v247, 0x3a800000, v205
	v_fmamk_f32 v248, v248, 0x3a800000, v205
	v_fmamk_f32 v249, v249, 0x3a800000, v205
	v_rsq_f32_e32 v242, v242
	v_rsq_f32_e32 v243, v243
	v_rsq_f32_e32 v244, v244
	v_rsq_f32_e32 v245, v245
	v_rsq_f32_e32 v246, v246
	v_rsq_f32_e32 v247, v247
	v_rsq_f32_e32 v248, v248
	v_rsq_f32_e32 v249, v249
	v_mov_b32_e32 v201, v200
	v_mov_b32_e32 v202, v251
	v_mov_b32_e32 v228, v242
	s_cmp_lt_u32 s0, 64
	s_cbranch_scc0 .Lrn_xdone_0
	global_store_dwordx4 v201, v[150:153], s[52:53] nt
	global_store_dwordx4 v201, v[146:149], s[52:53] offset:16 nt
	global_store_dwordx4 v201, v[154:157], s[52:53] offset:512 nt
	global_store_dwordx4 v201, v[158:161], s[52:53] offset:528 nt
.Lrn_xdone_0:
	v_pk_mul_f32 v[168:169], v[150:151], v[228:229] op_sel_hi:[1,0]
	v_pk_mul_f32 v[170:171], v[152:153], v[228:229] op_sel_hi:[1,0]
	v_pk_mul_f32 v[172:173], v[146:147], v[228:229] op_sel_hi:[1,0]
	v_pk_mul_f32 v[174:175], v[148:149], v[228:229] op_sel_hi:[1,0]
	v_pk_mul_f32 v[176:177], v[154:155], v[228:229] op_sel_hi:[1,0]
	v_pk_mul_f32 v[178:179], v[156:157], v[228:229] op_sel_hi:[1,0]
	v_pk_mul_f32 v[180:181], v[158:159], v[228:229] op_sel_hi:[1,0]
	v_pk_mul_f32 v[182:183], v[160:161], v[228:229] op_sel_hi:[1,0]
	v_pk_mul_f32 v[184:185], v[122:123], v[168:169]
	v_pk_mul_f32 v[186:187], v[124:125], v[170:171]
	v_pk_mul_f32 v[188:189], v[118:119], v[172:173]
	v_pk_mul_f32 v[190:191], v[120:121], v[174:175]
	v_pk_mul_f32 v[192:193], v[110:111], v[176:177]
	v_pk_mul_f32 v[194:195], v[112:113], v[178:179]
	v_pk_mul_f32 v[196:197], v[106:107], v[180:181]
	v_pk_mul_f32 v[198:199], v[108:109], v[182:183]
	v_cvt_pk_bf16_f32 v184, v184, v185
	v_cvt_pk_bf16_f32 v185, v186, v187
	v_cvt_pk_bf16_f32 v186, v188, v189
	v_cvt_pk_bf16_f32 v187, v190, v191
	global_store_dwordx4 v202, v[184:187], s[50:51]
	v_cvt_pk_bf16_f32 v192, v192, v193
	v_cvt_pk_bf16_f32 v193, v194, v195
	v_cvt_pk_bf16_f32 v194, v196, v197
	v_cvt_pk_bf16_f32 v195, v198, v199
	global_store_dwordx4 v202, v[192:195], s[50:51] offset:256
	s_and_b64 vcc, exec, s[8:9]
	s_cbranch_vccz .Lrn_nodual_0
	v_pk_mul_f32 v[210:211], v[114:115], v[168:169]
	v_pk_mul_f32 v[212:213], v[116:117], v[170:171]
	v_pk_mul_f32 v[214:215], v[126:127], v[172:173]
	v_pk_mul_f32 v[216:217], v[128:129], v[174:175]
	v_pk_mul_f32 v[218:219], v[98:99], v[176:177]
	v_pk_mul_f32 v[220:221], v[100:101], v[178:179]
	v_pk_mul_f32 v[222:223], v[102:103], v[180:181]
	v_pk_mul_f32 v[224:225], v[104:105], v[182:183]
	v_cvt_pk_bf16_f32 v210, v210, v211
	v_cvt_pk_bf16_f32 v211, v212, v213
	v_cvt_pk_bf16_f32 v212, v214, v215
	v_cvt_pk_bf16_f32 v213, v216, v217
	global_store_dwordx4 v202, v[210:213], s[6:7]
	v_cvt_pk_bf16_f32 v218, v218, v219
	v_cvt_pk_bf16_f32 v219, v220, v221
	v_cvt_pk_bf16_f32 v220, v222, v223
	v_cvt_pk_bf16_f32 v221, v224, v225
	global_store_dwordx4 v202, v[218:221], s[6:7] offset:256
.Lrn_nodual_0:
	v_add_u32_e32 v201, 0x10000, v200
	v_add_u32_e32 v202, 0x8000, v251
	v_mov_b32_e32 v228, v243
	s_cmp_lt_u32 s0, 64
	s_cbranch_scc0 .Lrn_xdone_1
	global_store_dwordx4 v201, v[134:137], s[52:53] nt
	global_store_dwordx4 v201, v[130:133], s[52:53] offset:16 nt
	global_store_dwordx4 v201, v[138:141], s[52:53] offset:512 nt
	global_store_dwordx4 v201, v[142:145], s[52:53] offset:528 nt
.Lrn_xdone_1:
	v_pk_mul_f32 v[168:169], v[134:135], v[228:229] op_sel_hi:[1,0]
	v_pk_mul_f32 v[170:171], v[136:137], v[228:229] op_sel_hi:[1,0]
	v_pk_mul_f32 v[172:173], v[130:131], v[228:229] op_sel_hi:[1,0]
	v_pk_mul_f32 v[174:175], v[132:133], v[228:229] op_sel_hi:[1,0]
	v_pk_mul_f32 v[176:177], v[138:139], v[228:229] op_sel_hi:[1,0]
	v_pk_mul_f32 v[178:179], v[140:141], v[228:229] op_sel_hi:[1,0]
	v_pk_mul_f32 v[180:181], v[142:143], v[228:229] op_sel_hi:[1,0]
	v_pk_mul_f32 v[182:183], v[144:145], v[228:229] op_sel_hi:[1,0]
	v_pk_mul_f32 v[184:185], v[122:123], v[168:169]
	v_pk_mul_f32 v[186:187], v[124:125], v[170:171]
	v_pk_mul_f32 v[188:189], v[118:119], v[172:173]
	v_pk_mul_f32 v[190:191], v[120:121], v[174:175]
	v_pk_mul_f32 v[192:193], v[110:111], v[176:177]
	v_pk_mul_f32 v[194:195], v[112:113], v[178:179]
	v_pk_mul_f32 v[196:197], v[106:107], v[180:181]
	v_pk_mul_f32 v[198:199], v[108:109], v[182:183]
	v_cvt_pk_bf16_f32 v184, v184, v185
	v_cvt_pk_bf16_f32 v185, v186, v187
	v_cvt_pk_bf16_f32 v186, v188, v189
	v_cvt_pk_bf16_f32 v187, v190, v191
	global_store_dwordx4 v202, v[184:187], s[50:51]
	v_cvt_pk_bf16_f32 v192, v192, v193
	v_cvt_pk_bf16_f32 v193, v194, v195
	v_cvt_pk_bf16_f32 v194, v196, v197
	v_cvt_pk_bf16_f32 v195, v198, v199
	global_store_dwordx4 v202, v[192:195], s[50:51] offset:256
	s_and_b64 vcc, exec, s[8:9]
	s_cbranch_vccz .Lrn_nodual_1
	v_pk_mul_f32 v[210:211], v[114:115], v[168:169]
	v_pk_mul_f32 v[212:213], v[116:117], v[170:171]
	v_pk_mul_f32 v[214:215], v[126:127], v[172:173]
	v_pk_mul_f32 v[216:217], v[128:129], v[174:175]
	v_pk_mul_f32 v[218:219], v[98:99], v[176:177]
	v_pk_mul_f32 v[220:221], v[100:101], v[178:179]
	v_pk_mul_f32 v[222:223], v[102:103], v[180:181]
	v_pk_mul_f32 v[224:225], v[104:105], v[182:183]
	v_cvt_pk_bf16_f32 v210, v210, v211
	v_cvt_pk_bf16_f32 v211, v212, v213
	v_cvt_pk_bf16_f32 v212, v214, v215
	v_cvt_pk_bf16_f32 v213, v216, v217
	global_store_dwordx4 v202, v[210:213], s[6:7]
	v_cvt_pk_bf16_f32 v218, v218, v219
	v_cvt_pk_bf16_f32 v219, v220, v221
	v_cvt_pk_bf16_f32 v220, v222, v223
	v_cvt_pk_bf16_f32 v221, v224, v225
	global_store_dwordx4 v202, v[218:221], s[6:7] offset:256
.Lrn_nodual_1:
	v_add_u32_e32 v201, 0x20000, v200
	v_add_u32_e32 v202, 0x10000, v251
	v_mov_b32_e32 v228, v244
	s_cmp_lt_u32 s0, 64
	s_cbranch_scc0 .Lrn_xdone_2
	global_store_dwordx4 v201, v[86:89], s[52:53] nt
	global_store_dwordx4 v201, v[82:85], s[52:53] offset:16 nt
	global_store_dwordx4 v201, v[90:93], s[52:53] offset:512 nt
	global_store_dwordx4 v201, v[94:97], s[52:53] offset:528 nt
.Lrn_xdone_2:
	v_pk_mul_f32 v[168:169], v[86:87], v[228:229] op_sel_hi:[1,0]
	v_pk_mul_f32 v[170:171], v[88:89], v[228:229] op_sel_hi:[1,0]
	v_pk_mul_f32 v[172:173], v[82:83], v[228:229] op_sel_hi:[1,0]
	v_pk_mul_f32 v[174:175], v[84:85], v[228:229] op_sel_hi:[1,0]
	v_pk_mul_f32 v[176:177], v[90:91], v[228:229] op_sel_hi:[1,0]
	v_pk_mul_f32 v[178:179], v[92:93], v[228:229] op_sel_hi:[1,0]
	v_pk_mul_f32 v[180:181], v[94:95], v[228:229] op_sel_hi:[1,0]
	v_pk_mul_f32 v[182:183], v[96:97], v[228:229] op_sel_hi:[1,0]
	v_pk_mul_f32 v[184:185], v[122:123], v[168:169]
	v_pk_mul_f32 v[186:187], v[124:125], v[170:171]
	v_pk_mul_f32 v[188:189], v[118:119], v[172:173]
	v_pk_mul_f32 v[190:191], v[120:121], v[174:175]
	v_pk_mul_f32 v[192:193], v[110:111], v[176:177]
	v_pk_mul_f32 v[194:195], v[112:113], v[178:179]
	v_pk_mul_f32 v[196:197], v[106:107], v[180:181]
	v_pk_mul_f32 v[198:199], v[108:109], v[182:183]
	v_cvt_pk_bf16_f32 v184, v184, v185
	v_cvt_pk_bf16_f32 v185, v186, v187
	v_cvt_pk_bf16_f32 v186, v188, v189
	v_cvt_pk_bf16_f32 v187, v190, v191
	global_store_dwordx4 v202, v[184:187], s[50:51]
	v_cvt_pk_bf16_f32 v192, v192, v193
	v_cvt_pk_bf16_f32 v193, v194, v195
	v_cvt_pk_bf16_f32 v194, v196, v197
	v_cvt_pk_bf16_f32 v195, v198, v199
	global_store_dwordx4 v202, v[192:195], s[50:51] offset:256
	s_and_b64 vcc, exec, s[8:9]
	s_cbranch_vccz .Lrn_nodual_2
	v_pk_mul_f32 v[210:211], v[114:115], v[168:169]
	v_pk_mul_f32 v[212:213], v[116:117], v[170:171]
	v_pk_mul_f32 v[214:215], v[126:127], v[172:173]
	v_pk_mul_f32 v[216:217], v[128:129], v[174:175]
	v_pk_mul_f32 v[218:219], v[98:99], v[176:177]
	v_pk_mul_f32 v[220:221], v[100:101], v[178:179]
	v_pk_mul_f32 v[222:223], v[102:103], v[180:181]
	v_pk_mul_f32 v[224:225], v[104:105], v[182:183]
	v_cvt_pk_bf16_f32 v210, v210, v211
	v_cvt_pk_bf16_f32 v211, v212, v213
	v_cvt_pk_bf16_f32 v212, v214, v215
	v_cvt_pk_bf16_f32 v213, v216, v217
	global_store_dwordx4 v202, v[210:213], s[6:7]
	v_cvt_pk_bf16_f32 v218, v218, v219
	v_cvt_pk_bf16_f32 v219, v220, v221
	v_cvt_pk_bf16_f32 v220, v222, v223
	v_cvt_pk_bf16_f32 v221, v224, v225
	global_store_dwordx4 v202, v[218:221], s[6:7] offset:256
.Lrn_nodual_2:
	v_add_u32_e32 v201, 0x30000, v200
	v_add_u32_e32 v202, 0x18000, v251
	v_mov_b32_e32 v228, v245
	s_cmp_lt_u32 s0, 64
	s_cbranch_scc0 .Lrn_xdone_3
	global_store_dwordx4 v201, v[70:73], s[52:53] nt
	global_store_dwordx4 v201, v[66:69], s[52:53] offset:16 nt
	global_store_dwordx4 v201, v[74:77], s[52:53] offset:512 nt
	global_store_dwordx4 v201, v[78:81], s[52:53] offset:528 nt
.Lrn_xdone_3:
	v_pk_mul_f32 v[168:169], v[70:71], v[228:229] op_sel_hi:[1,0]
	v_pk_mul_f32 v[170:171], v[72:73], v[228:229] op_sel_hi:[1,0]
	v_pk_mul_f32 v[172:173], v[66:67], v[228:229] op_sel_hi:[1,0]
	v_pk_mul_f32 v[174:175], v[68:69], v[228:229] op_sel_hi:[1,0]
	v_pk_mul_f32 v[176:177], v[74:75], v[228:229] op_sel_hi:[1,0]
	v_pk_mul_f32 v[178:179], v[76:77], v[228:229] op_sel_hi:[1,0]
	v_pk_mul_f32 v[180:181], v[78:79], v[228:229] op_sel_hi:[1,0]
	v_pk_mul_f32 v[182:183], v[80:81], v[228:229] op_sel_hi:[1,0]
	v_pk_mul_f32 v[184:185], v[122:123], v[168:169]
	v_pk_mul_f32 v[186:187], v[124:125], v[170:171]
	v_pk_mul_f32 v[188:189], v[118:119], v[172:173]
	v_pk_mul_f32 v[190:191], v[120:121], v[174:175]
	v_pk_mul_f32 v[192:193], v[110:111], v[176:177]
	v_pk_mul_f32 v[194:195], v[112:113], v[178:179]
	v_pk_mul_f32 v[196:197], v[106:107], v[180:181]
	v_pk_mul_f32 v[198:199], v[108:109], v[182:183]
	v_cvt_pk_bf16_f32 v184, v184, v185
	v_cvt_pk_bf16_f32 v185, v186, v187
	v_cvt_pk_bf16_f32 v186, v188, v189
	v_cvt_pk_bf16_f32 v187, v190, v191
	global_store_dwordx4 v202, v[184:187], s[50:51]
	v_cvt_pk_bf16_f32 v192, v192, v193
	v_cvt_pk_bf16_f32 v193, v194, v195
	v_cvt_pk_bf16_f32 v194, v196, v197
	v_cvt_pk_bf16_f32 v195, v198, v199
	global_store_dwordx4 v202, v[192:195], s[50:51] offset:256
	s_and_b64 vcc, exec, s[8:9]
	s_cbranch_vccz .Lrn_nodual_3
	v_pk_mul_f32 v[210:211], v[114:115], v[168:169]
	v_pk_mul_f32 v[212:213], v[116:117], v[170:171]
	v_pk_mul_f32 v[214:215], v[126:127], v[172:173]
	v_pk_mul_f32 v[216:217], v[128:129], v[174:175]
	v_pk_mul_f32 v[218:219], v[98:99], v[176:177]
	v_pk_mul_f32 v[220:221], v[100:101], v[178:179]
	v_pk_mul_f32 v[222:223], v[102:103], v[180:181]
	v_pk_mul_f32 v[224:225], v[104:105], v[182:183]
	v_cvt_pk_bf16_f32 v210, v210, v211
	v_cvt_pk_bf16_f32 v211, v212, v213
	v_cvt_pk_bf16_f32 v212, v214, v215
	v_cvt_pk_bf16_f32 v213, v216, v217
	global_store_dwordx4 v202, v[210:213], s[6:7]
	v_cvt_pk_bf16_f32 v218, v218, v219
	v_cvt_pk_bf16_f32 v219, v220, v221
	v_cvt_pk_bf16_f32 v220, v222, v223
	v_cvt_pk_bf16_f32 v221, v224, v225
	global_store_dwordx4 v202, v[218:221], s[6:7] offset:256
.Lrn_nodual_3:
	v_add_u32_e32 v201, 0x80000, v200
	v_add_u32_e32 v202, 0x40000, v251
	v_mov_b32_e32 v228, v246
	s_cmp_lt_u32 s0, 64
	s_cbranch_scc0 .Lrn_xdone_4
	global_store_dwordx4 v201, v[54:57], s[52:53] nt
	global_store_dwordx4 v201, v[50:53], s[52:53] offset:16 nt
	global_store_dwordx4 v201, v[58:61], s[52:53] offset:512 nt
	global_store_dwordx4 v201, v[62:65], s[52:53] offset:528 nt
.Lrn_xdone_4:
	v_pk_mul_f32 v[168:169], v[54:55], v[228:229] op_sel_hi:[1,0]
	v_pk_mul_f32 v[170:171], v[56:57], v[228:229] op_sel_hi:[1,0]
	v_pk_mul_f32 v[172:173], v[50:51], v[228:229] op_sel_hi:[1,0]
	v_pk_mul_f32 v[174:175], v[52:53], v[228:229] op_sel_hi:[1,0]
	v_pk_mul_f32 v[176:177], v[58:59], v[228:229] op_sel_hi:[1,0]
	v_pk_mul_f32 v[178:179], v[60:61], v[228:229] op_sel_hi:[1,0]
	v_pk_mul_f32 v[180:181], v[62:63], v[228:229] op_sel_hi:[1,0]
	v_pk_mul_f32 v[182:183], v[64:65], v[228:229] op_sel_hi:[1,0]
	v_pk_mul_f32 v[184:185], v[122:123], v[168:169]
	v_pk_mul_f32 v[186:187], v[124:125], v[170:171]
	v_pk_mul_f32 v[188:189], v[118:119], v[172:173]
	v_pk_mul_f32 v[190:191], v[120:121], v[174:175]
	v_pk_mul_f32 v[192:193], v[110:111], v[176:177]
	v_pk_mul_f32 v[194:195], v[112:113], v[178:179]
	v_pk_mul_f32 v[196:197], v[106:107], v[180:181]
	v_pk_mul_f32 v[198:199], v[108:109], v[182:183]
	v_cvt_pk_bf16_f32 v184, v184, v185
	v_cvt_pk_bf16_f32 v185, v186, v187
	v_cvt_pk_bf16_f32 v186, v188, v189
	v_cvt_pk_bf16_f32 v187, v190, v191
	global_store_dwordx4 v202, v[184:187], s[50:51]
	v_cvt_pk_bf16_f32 v192, v192, v193
	v_cvt_pk_bf16_f32 v193, v194, v195
	v_cvt_pk_bf16_f32 v194, v196, v197
	v_cvt_pk_bf16_f32 v195, v198, v199
	global_store_dwordx4 v202, v[192:195], s[50:51] offset:256
	s_and_b64 vcc, exec, s[8:9]
	s_cbranch_vccz .Lrn_nodual_4
	v_pk_mul_f32 v[210:211], v[114:115], v[168:169]
	v_pk_mul_f32 v[212:213], v[116:117], v[170:171]
	v_pk_mul_f32 v[214:215], v[126:127], v[172:173]
	v_pk_mul_f32 v[216:217], v[128:129], v[174:175]
	v_pk_mul_f32 v[218:219], v[98:99], v[176:177]
	v_pk_mul_f32 v[220:221], v[100:101], v[178:179]
	v_pk_mul_f32 v[222:223], v[102:103], v[180:181]
	v_pk_mul_f32 v[224:225], v[104:105], v[182:183]
	v_cvt_pk_bf16_f32 v210, v210, v211
	v_cvt_pk_bf16_f32 v211, v212, v213
	v_cvt_pk_bf16_f32 v212, v214, v215
	v_cvt_pk_bf16_f32 v213, v216, v217
	global_store_dwordx4 v202, v[210:213], s[6:7]
	v_cvt_pk_bf16_f32 v218, v218, v219
	v_cvt_pk_bf16_f32 v219, v220, v221
	v_cvt_pk_bf16_f32 v220, v222, v223
	v_cvt_pk_bf16_f32 v221, v224, v225
	global_store_dwordx4 v202, v[218:221], s[6:7] offset:256
.Lrn_nodual_4:
	v_add_u32_e32 v201, 0x90000, v200
	v_add_u32_e32 v202, 0x48000, v251
	v_mov_b32_e32 v228, v247
	s_cmp_lt_u32 s0, 64
	s_cbranch_scc0 .Lrn_xdone_5
	global_store_dwordx4 v201, v[38:41], s[52:53] nt
	global_store_dwordx4 v201, v[34:37], s[52:53] offset:16 nt
	global_store_dwordx4 v201, v[42:45], s[52:53] offset:512 nt
	global_store_dwordx4 v201, v[46:49], s[52:53] offset:528 nt
.Lrn_xdone_5:
	v_pk_mul_f32 v[168:169], v[38:39], v[228:229] op_sel_hi:[1,0]
	v_pk_mul_f32 v[170:171], v[40:41], v[228:229] op_sel_hi:[1,0]
	v_pk_mul_f32 v[172:173], v[34:35], v[228:229] op_sel_hi:[1,0]
	v_pk_mul_f32 v[174:175], v[36:37], v[228:229] op_sel_hi:[1,0]
	v_pk_mul_f32 v[176:177], v[42:43], v[228:229] op_sel_hi:[1,0]
	v_pk_mul_f32 v[178:179], v[44:45], v[228:229] op_sel_hi:[1,0]
	v_pk_mul_f32 v[180:181], v[46:47], v[228:229] op_sel_hi:[1,0]
	v_pk_mul_f32 v[182:183], v[48:49], v[228:229] op_sel_hi:[1,0]
	v_pk_mul_f32 v[184:185], v[122:123], v[168:169]
	v_pk_mul_f32 v[186:187], v[124:125], v[170:171]
	v_pk_mul_f32 v[188:189], v[118:119], v[172:173]
	v_pk_mul_f32 v[190:191], v[120:121], v[174:175]
	v_pk_mul_f32 v[192:193], v[110:111], v[176:177]
	v_pk_mul_f32 v[194:195], v[112:113], v[178:179]
	v_pk_mul_f32 v[196:197], v[106:107], v[180:181]
	v_pk_mul_f32 v[198:199], v[108:109], v[182:183]
	v_cvt_pk_bf16_f32 v184, v184, v185
	v_cvt_pk_bf16_f32 v185, v186, v187
	v_cvt_pk_bf16_f32 v186, v188, v189
	v_cvt_pk_bf16_f32 v187, v190, v191
	global_store_dwordx4 v202, v[184:187], s[50:51]
	v_cvt_pk_bf16_f32 v192, v192, v193
	v_cvt_pk_bf16_f32 v193, v194, v195
	v_cvt_pk_bf16_f32 v194, v196, v197
	v_cvt_pk_bf16_f32 v195, v198, v199
	global_store_dwordx4 v202, v[192:195], s[50:51] offset:256
	s_and_b64 vcc, exec, s[8:9]
	s_cbranch_vccz .Lrn_nodual_5
	v_pk_mul_f32 v[210:211], v[114:115], v[168:169]
	v_pk_mul_f32 v[212:213], v[116:117], v[170:171]
	v_pk_mul_f32 v[214:215], v[126:127], v[172:173]
	v_pk_mul_f32 v[216:217], v[128:129], v[174:175]
	v_pk_mul_f32 v[218:219], v[98:99], v[176:177]
	v_pk_mul_f32 v[220:221], v[100:101], v[178:179]
	v_pk_mul_f32 v[222:223], v[102:103], v[180:181]
	v_pk_mul_f32 v[224:225], v[104:105], v[182:183]
	v_cvt_pk_bf16_f32 v210, v210, v211
	v_cvt_pk_bf16_f32 v211, v212, v213
	v_cvt_pk_bf16_f32 v212, v214, v215
	v_cvt_pk_bf16_f32 v213, v216, v217
	global_store_dwordx4 v202, v[210:213], s[6:7]
	v_cvt_pk_bf16_f32 v218, v218, v219
	v_cvt_pk_bf16_f32 v219, v220, v221
	v_cvt_pk_bf16_f32 v220, v222, v223
	v_cvt_pk_bf16_f32 v221, v224, v225
	global_store_dwordx4 v202, v[218:221], s[6:7] offset:256
.Lrn_nodual_5:
	v_add_u32_e32 v201, 0xa0000, v200
	v_add_u32_e32 v202, 0x50000, v251
	v_mov_b32_e32 v228, v248
	s_cmp_lt_u32 s0, 64
	s_cbranch_scc0 .Lrn_xdone_6
	global_store_dwordx4 v201, v[22:25], s[52:53] nt
	global_store_dwordx4 v201, v[18:21], s[52:53] offset:16 nt
	global_store_dwordx4 v201, v[26:29], s[52:53] offset:512 nt
	global_store_dwordx4 v201, v[30:33], s[52:53] offset:528 nt
.Lrn_xdone_6:
	v_pk_mul_f32 v[168:169], v[22:23], v[228:229] op_sel_hi:[1,0]
	v_pk_mul_f32 v[170:171], v[24:25], v[228:229] op_sel_hi:[1,0]
	v_pk_mul_f32 v[172:173], v[18:19], v[228:229] op_sel_hi:[1,0]
	v_pk_mul_f32 v[174:175], v[20:21], v[228:229] op_sel_hi:[1,0]
	v_pk_mul_f32 v[176:177], v[26:27], v[228:229] op_sel_hi:[1,0]
	v_pk_mul_f32 v[178:179], v[28:29], v[228:229] op_sel_hi:[1,0]
	v_pk_mul_f32 v[180:181], v[30:31], v[228:229] op_sel_hi:[1,0]
	v_pk_mul_f32 v[182:183], v[32:33], v[228:229] op_sel_hi:[1,0]
	v_pk_mul_f32 v[184:185], v[122:123], v[168:169]
	v_pk_mul_f32 v[186:187], v[124:125], v[170:171]
	v_pk_mul_f32 v[188:189], v[118:119], v[172:173]
	v_pk_mul_f32 v[190:191], v[120:121], v[174:175]
	v_pk_mul_f32 v[192:193], v[110:111], v[176:177]
	v_pk_mul_f32 v[194:195], v[112:113], v[178:179]
	v_pk_mul_f32 v[196:197], v[106:107], v[180:181]
	v_pk_mul_f32 v[198:199], v[108:109], v[182:183]
	v_cvt_pk_bf16_f32 v184, v184, v185
	v_cvt_pk_bf16_f32 v185, v186, v187
	v_cvt_pk_bf16_f32 v186, v188, v189
	v_cvt_pk_bf16_f32 v187, v190, v191
	global_store_dwordx4 v202, v[184:187], s[50:51]
	v_cvt_pk_bf16_f32 v192, v192, v193
	v_cvt_pk_bf16_f32 v193, v194, v195
	v_cvt_pk_bf16_f32 v194, v196, v197
	v_cvt_pk_bf16_f32 v195, v198, v199
	global_store_dwordx4 v202, v[192:195], s[50:51] offset:256
	s_and_b64 vcc, exec, s[8:9]
	s_cbranch_vccz .Lrn_nodual_6
	v_pk_mul_f32 v[210:211], v[114:115], v[168:169]
	v_pk_mul_f32 v[212:213], v[116:117], v[170:171]
	v_pk_mul_f32 v[214:215], v[126:127], v[172:173]
	v_pk_mul_f32 v[216:217], v[128:129], v[174:175]
	v_pk_mul_f32 v[218:219], v[98:99], v[176:177]
	v_pk_mul_f32 v[220:221], v[100:101], v[178:179]
	v_pk_mul_f32 v[222:223], v[102:103], v[180:181]
	v_pk_mul_f32 v[224:225], v[104:105], v[182:183]
	v_cvt_pk_bf16_f32 v210, v210, v211
	v_cvt_pk_bf16_f32 v211, v212, v213
	v_cvt_pk_bf16_f32 v212, v214, v215
	v_cvt_pk_bf16_f32 v213, v216, v217
	global_store_dwordx4 v202, v[210:213], s[6:7]
	v_cvt_pk_bf16_f32 v218, v218, v219
	v_cvt_pk_bf16_f32 v219, v220, v221
	v_cvt_pk_bf16_f32 v220, v222, v223
	v_cvt_pk_bf16_f32 v221, v224, v225
	global_store_dwordx4 v202, v[218:221], s[6:7] offset:256
.Lrn_nodual_6:
	v_add_u32_e32 v201, 0xb0000, v200
	v_add_u32_e32 v202, 0x58000, v251
	v_mov_b32_e32 v228, v249
	s_cmp_lt_u32 s0, 64
	s_cbranch_scc0 .Lrn_xdone_7
	global_store_dwordx4 v201, v[6:9], s[52:53] nt
	global_store_dwordx4 v201, v[2:5], s[52:53] offset:16 nt
	global_store_dwordx4 v201, v[10:13], s[52:53] offset:512 nt
	global_store_dwordx4 v201, v[14:17], s[52:53] offset:528 nt
.Lrn_xdone_7:
	v_pk_mul_f32 v[168:169], v[6:7], v[228:229] op_sel_hi:[1,0]
	v_pk_mul_f32 v[170:171], v[8:9], v[228:229] op_sel_hi:[1,0]
	v_pk_mul_f32 v[172:173], v[2:3], v[228:229] op_sel_hi:[1,0]
	v_pk_mul_f32 v[174:175], v[4:5], v[228:229] op_sel_hi:[1,0]
	v_pk_mul_f32 v[176:177], v[10:11], v[228:229] op_sel_hi:[1,0]
	v_pk_mul_f32 v[178:179], v[12:13], v[228:229] op_sel_hi:[1,0]
	v_pk_mul_f32 v[180:181], v[14:15], v[228:229] op_sel_hi:[1,0]
	v_pk_mul_f32 v[182:183], v[16:17], v[228:229] op_sel_hi:[1,0]
	v_pk_mul_f32 v[184:185], v[122:123], v[168:169]
	v_pk_mul_f32 v[186:187], v[124:125], v[170:171]
	v_pk_mul_f32 v[188:189], v[118:119], v[172:173]
	v_pk_mul_f32 v[190:191], v[120:121], v[174:175]
	v_pk_mul_f32 v[192:193], v[110:111], v[176:177]
	v_pk_mul_f32 v[194:195], v[112:113], v[178:179]
	v_pk_mul_f32 v[196:197], v[106:107], v[180:181]
	v_pk_mul_f32 v[198:199], v[108:109], v[182:183]
	v_cvt_pk_bf16_f32 v184, v184, v185
	v_cvt_pk_bf16_f32 v185, v186, v187
	v_cvt_pk_bf16_f32 v186, v188, v189
	v_cvt_pk_bf16_f32 v187, v190, v191
	global_store_dwordx4 v202, v[184:187], s[50:51]
	v_cvt_pk_bf16_f32 v192, v192, v193
	v_cvt_pk_bf16_f32 v193, v194, v195
	v_cvt_pk_bf16_f32 v194, v196, v197
	v_cvt_pk_bf16_f32 v195, v198, v199
	global_store_dwordx4 v202, v[192:195], s[50:51] offset:256
	s_and_b64 vcc, exec, s[8:9]
	s_cbranch_vccz .Lrn_nodual_7
	v_pk_mul_f32 v[210:211], v[114:115], v[168:169]
	v_pk_mul_f32 v[212:213], v[116:117], v[170:171]
	v_pk_mul_f32 v[214:215], v[126:127], v[172:173]
	v_pk_mul_f32 v[216:217], v[128:129], v[174:175]
	v_pk_mul_f32 v[218:219], v[98:99], v[176:177]
	v_pk_mul_f32 v[220:221], v[100:101], v[178:179]
	v_pk_mul_f32 v[222:223], v[102:103], v[180:181]
	v_pk_mul_f32 v[224:225], v[104:105], v[182:183]
	v_cvt_pk_bf16_f32 v210, v210, v211
	v_cvt_pk_bf16_f32 v211, v212, v213
	v_cvt_pk_bf16_f32 v212, v214, v215
	v_cvt_pk_bf16_f32 v213, v216, v217
	global_store_dwordx4 v202, v[210:213], s[6:7]
	v_cvt_pk_bf16_f32 v218, v218, v219
	v_cvt_pk_bf16_f32 v219, v220, v221
	v_cvt_pk_bf16_f32 v220, v222, v223
	v_cvt_pk_bf16_f32 v221, v224, v225
	global_store_dwordx4 v202, v[218:221], s[6:7] offset:256
